# sc1 epilogue stores + xch combine loads issued together + scan G-tile LDS reads issued up front (counted lgkmcnt)
# baseline (speedup 1.0000x reference)
;     __device__ __forceinline__ void fused(f32x4 (&acc)[2][2][4][2], const pg8::Unit& u, int wr, int wc, int fr, int fq, LAS unsigned char* lds, int wid, int lane) const {
;     ...
;         asm volatile("s_waitcnt lgkmcnt(0)" ::: "memory"); __builtin_amdgcn_s_barrier(); asm volatile("" ::: "memory");
;         if (tid < 256) {
;             float t = 0.f;
; #pragma unroll
;             for (int k = 0; k < 4; ++k) t += __hip_atomic_load(xch + ((size_t)u.pm * 4 + k) * 256 + tid, __ATOMIC_RELAXED, __HIP_MEMORY_SCOPE_AGENT);
;             S[tid] = rsqrtf(t * (1.0f / 1024.f) + EPS_);
;         }
;         asm volatile("s_waitcnt vmcnt(0) lgkmcnt(0)" ::: "memory"); __builtin_amdgcn_s_barrier(); asm volatile("" ::: "memory");
.LBB0_605:
	s_waitcnt lgkmcnt(0)
	s_barrier
	s_and_saveexec_b64 s[0:1], s[6:7]
	s_cbranch_execz .LBB0_607
	s_ashr_i32 s75, s74, 31
	s_lshl_b64 s[8:9], s[74:75], 12
	v_readlane_b32 s10, v254, 19
	s_add_u32 s8, s10, s8
	v_readlane_b32 s10, v254, 20
	s_addc_u32 s9, s10, s9
	v_lshl_add_u64 v[10:11], v[4:5], 2, s[8:9]
	global_load_dword v5, v[10:11], off sc1
	global_load_dword v12, v[10:11], off offset:1024 sc1
	global_load_dword v13, v[10:11], off offset:2048 sc1
	global_load_dword v14, v[10:11], off offset:3072 sc1
	s_mov_b32 s8, 0x800000
	s_waitcnt vmcnt(0)
	v_add_f32_e32 v5, 0, v5
	v_add_f32_e32 v5, v5, v12
	v_add_f32_e32 v5, v5, v13
	v_add_f32_e32 v5, v5, v14
	v_fmamk_f32 v5, v5, 0x3a800000, v170
	v_cmp_gt_f32_e32 vcc, s8, v5
	v_mul_f32_e32 v10, 0x4b800000, v5
	s_nop 0
	v_cndmask_b32_e32 v5, v5, v10, vcc
	v_rsq_f32_e32 v5, v5
	s_nop 0
	v_mul_f32_e32 v10, 0x45800000, v5
	v_cndmask_b32_e32 v5, v5, v10, vcc
	v_lshl_add_u32 v10, v4, 2, 0
	ds_write_b32 v10, v5 offset:4096

; #define LAS __attribute__((address_space(3)))
; __device__ __forceinline__ unsigned pk2(float lo, float hi) { unsigned r; asm volatile("v_cvt_pk_bf16_f32 %0, %1, %2" : "=v"(r) : "v"(lo), "v"(hi)); return r; }
; template <bool DRY>
; __device__ __forceinline__ void ssd_chunk(SsdRegs& R, f32x4 (&st)[2], LAS unsigned char* L, bf16_t* BIG, const float* DT, float* SSQY, const SsdItem& I, int c, int tid, int lane, int wave, int li, int pi, int c16, int q4) {
;     ...
;     {
;         const int l = 16 * li + c16; const float acs_l = *(const LAS float*)(SCW + l * 4);
; #pragma unroll
;         for (int t = 0; t < 2; ++t) {
;             const int si = 2 * pi + t;
;             u32x2 w; w.x = 0u; w.y = 0u;
;             if (si <= li) {
;                 f32x4 d = (f32x4){0.f, 0.f, 0.f, 0.f};
; #pragma unroll
;                 for (int kk = 0; kk < 4; ++kk) d = __builtin_amdgcn_mfma_f32_16x16x32_bf16(SSD_FRAG(BS, PC, 16 * si, kk), cfr[kk], d, 0, 0, 0);
;                 float gv[4];
;                 const f32x4 acs_s = *(const LAS f32x4*)(SCW + (16 * si + 4 * q4) * 4), dt_s = *(const LAS f32x4*)(SCW + 256 + (16 * si + 4 * q4) * 4);
; #pragma unroll
;                 for (int e = 0; e < 4; ++e) gv[e] = d[e] * __expf(acs_l - acs_s[e]) * dt_s[e];
;                 if (si == li) {
; #pragma unroll
;                     for (int e = 0; e < 4; ++e) gv[e] = (4 * q4 + e <= c16) ? gv[e] : 0.f;
;                 }
;                 w.x = pk2(gv[0], gv[1]); w.y = pk2(gv[2], gv[3]);
;             }
;             *(LAS u32x2*)(L + GG + l * PT + (16 * si + 4 * q4) * 2) = w;
.LBB0_727:
	ds_read_b128 v[70:73], v131
	ds_read_b128 v[66:69], v131 offset:64
	ds_read_b128 v[62:65], v131 offset:128
	ds_read_b128 v[58:61], v131 offset:192
	ds_read_b32 v76, v132
	v_mov_b32_e32 v106, 0
	v_cndmask_b32_e64 v107, 0, 1, s[88:89]
	v_cmp_ne_u32_e64 s[22:23], 1, v107
	s_andn2_b64 vcc, exec, s[88:89]
	v_mov_b32_e32 v107, v106
	s_cbranch_vccnz .LBB0_729
	ds_read_b128 v[144:147], v133 offset:17408
	ds_read_b128 v[148:151], v133 offset:17472
	ds_read_b128 v[176:179], v133 offset:17536
	ds_read_b128 v[180:183], v133 offset:17600
	ds_read_b128 v[184:187], v134
	ds_read_b128 v[152:155], v134 offset:256
	s_waitcnt lgkmcnt(5)
	v_mfma_f32_16x16x32_bf16 v[144:147], v[144:147], v[70:73], 0
	s_waitcnt lgkmcnt(4)
	v_mfma_f32_16x16x32_bf16 v[144:147], v[148:151], v[66:69], v[144:147]
	s_waitcnt lgkmcnt(3)
	v_mfma_f32_16x16x32_bf16 v[144:147], v[176:179], v[62:65], v[144:147]
	s_waitcnt lgkmcnt(2)
	v_mfma_f32_16x16x32_bf16 v[144:147], v[180:183], v[58:61], v[144:147]
	s_waitcnt lgkmcnt(1)
	v_sub_f32_e32 v106, v76, v184
	v_sub_f32_e32 v107, v76, v185
	v_mul_f32_e32 v106, 0x3fb8aa3b, v106
	v_mul_f32_e32 v107, 0x3fb8aa3b, v107
	v_exp_f32_e32 v106, v106
	v_exp_f32_e32 v107, v107
	v_sub_f32_e32 v143, v76, v186
	v_mul_f32_e32 v143, 0x3fb8aa3b, v143
	v_pk_mul_f32 v[106:107], v[144:145], v[106:107]
	v_exp_f32_e32 v144, v143
	v_sub_f32_e32 v143, v76, v187
	v_mul_f32_e32 v143, 0x3fb8aa3b, v143
	v_exp_f32_e32 v145, v143
	s_waitcnt lgkmcnt(0)
	v_pk_mul_f32 v[106:107], v[152:153], v[106:107]
	v_pk_mul_f32 v[144:145], v[146:147], v[144:145]
	s_nop 0
	v_pk_mul_f32 v[144:145], v[154:155], v[144:145]
	v_cndmask_b32_e64 v143, v106, 0, s[6:7]
	v_cndmask_b32_e64 v146, 0, v107, s[8:9]
	v_cndmask_b32_e64 v147, v144, 0, s[10:11]
	v_cndmask_b32_e64 v148, v145, 0, s[12:13]
	v_cndmask_b32_e64 v106, v106, v143, s[4:5]
	v_cndmask_b32_e64 v107, v107, v146, s[4:5]
	v_cndmask_b32_e64 v144, v144, v147, s[4:5]
	v_cndmask_b32_e64 v145, v145, v148, s[4:5]
	v_cvt_pk_bf16_f32 v106, v106, v107
	v_cvt_pk_bf16_f32 v107, v144, v145

; #define LAS __attribute__((address_space(3)))
; __device__ __forceinline__ unsigned pk2(float lo, float hi) { unsigned r; asm volatile("v_cvt_pk_bf16_f32 %0, %1, %2" : "=v"(r) : "v"(lo), "v"(hi)); return r; }
; template <bool DRY>
; __device__ __forceinline__ void ssd_chunk(SsdRegs& R, f32x4 (&st)[2], LAS unsigned char* L, bf16_t* BIG, const float* DT, float* SSQY, const SsdItem& I, int c, int tid, int lane, int wave, int li, int pi, int c16, int q4) {
;     ...
;             if (si <= li) {
;                 f32x4 d = (f32x4){0.f, 0.f, 0.f, 0.f};
; #pragma unroll
;                 for (int kk = 0; kk < 4; ++kk) d = __builtin_amdgcn_mfma_f32_16x16x32_bf16(SSD_FRAG(BS, PC, 16 * si, kk), cfr[kk], d, 0, 0, 0);
;                 float gv[4];
;                 const f32x4 acs_s = *(const LAS f32x4*)(SCW + (16 * si + 4 * q4) * 4), dt_s = *(const LAS f32x4*)(SCW + 256 + (16 * si + 4 * q4) * 4);
; #pragma unroll
;                 for (int e = 0; e < 4; ++e) gv[e] = d[e] * __expf(acs_l - acs_s[e]) * dt_s[e];
;                 if (si == li) {
; #pragma unroll
;                     for (int e = 0; e < 4; ++e) gv[e] = (4 * q4 + e <= c16) ? gv[e] : 0.f;
;                 }
;                 w.x = pk2(gv[0], gv[1]); w.y = pk2(gv[2], gv[3]);
;             }
.LBB0_731:
	v_mov_b32_e32 v106, 0
	s_andn2_b64 vcc, exec, s[0:1]
	v_mov_b32_e32 v107, 0
	s_cbranch_vccnz .LBB0_733
	ds_read_b128 v[146:149], v135 offset:17408
	ds_read_b128 v[150:153], v135 offset:17472
	ds_read_b128 v[176:179], v135 offset:17536
	ds_read_b128 v[180:183], v135 offset:17600
	ds_read_b128 v[184:187], v136
	ds_read_b128 v[154:157], v136 offset:256
	s_waitcnt lgkmcnt(5)
	v_mfma_f32_16x16x32_bf16 v[146:149], v[146:149], v[70:73], 0
	s_waitcnt lgkmcnt(4)
	v_mfma_f32_16x16x32_bf16 v[146:149], v[150:153], v[66:69], v[146:149]
	s_waitcnt lgkmcnt(3)
	v_mfma_f32_16x16x32_bf16 v[146:149], v[176:179], v[62:65], v[146:149]
	s_waitcnt lgkmcnt(2)
	v_mfma_f32_16x16x32_bf16 v[146:149], v[180:183], v[58:61], v[146:149]
	s_waitcnt lgkmcnt(1)
	v_sub_f32_e32 v106, v76, v184
	v_sub_f32_e32 v107, v76, v185
	v_mul_f32_e32 v106, 0x3fb8aa3b, v106
	v_mul_f32_e32 v107, 0x3fb8aa3b, v107
	v_exp_f32_e32 v106, v106
	v_exp_f32_e32 v107, v107
	v_sub_f32_e32 v143, v76, v186
	v_sub_f32_e32 v76, v76, v187
	v_mul_f32_e32 v143, 0x3fb8aa3b, v143
	v_mul_f32_e32 v76, 0x3fb8aa3b, v76
	v_pk_mul_f32 v[106:107], v[146:147], v[106:107]
	v_exp_f32_e32 v146, v143
	v_exp_f32_e32 v147, v76
	s_waitcnt lgkmcnt(0)
	v_pk_mul_f32 v[106:107], v[154:155], v[106:107]
	v_pk_mul_f32 v[146:147], v[148:149], v[146:147]
	s_nop 0
	v_pk_mul_f32 v[146:147], v[156:157], v[146:147]
	v_cndmask_b32_e64 v76, v106, 0, s[6:7]
	v_cndmask_b32_e64 v143, 0, v107, s[8:9]
	v_cndmask_b32_e64 v145, v146, 0, s[10:11]
	v_cndmask_b32_e64 v148, v147, 0, s[12:13]
	v_cndmask_b32_e64 v76, v106, v76, s[14:15]
	v_cndmask_b32_e64 v106, v107, v143, s[14:15]
	v_cndmask_b32_e64 v145, v146, v145, s[14:15]
	v_cndmask_b32_e64 v146, v147, v148, s[14:15]
	v_cvt_pk_bf16_f32 v106, v76, v106
	v_cvt_pk_bf16_f32 v107, v145, v146

; #define LAS __attribute__((address_space(3)))
; __device__ __forceinline__ unsigned pk2(float lo, float hi) { unsigned r; asm volatile("v_cvt_pk_bf16_f32 %0, %1, %2" : "=v"(r) : "v"(lo), "v"(hi)); return r; }
; template <bool DRY>
; __device__ __forceinline__ void ssd_chunk(SsdRegs& R, f32x4 (&st)[2], LAS unsigned char* L, bf16_t* BIG, const float* DT, float* SSQY, const SsdItem& I, int c, int tid, int lane, int wave, int li, int pi, int c16, int q4) {
;     ...
;     for (int kk = 0; kk < 4; ++kk) cfr[kk] = SSD_FRAG(CS, PC, 16 * li, kk);
;     {
;         const int l = 16 * li + c16; const float acs_l = *(const LAS float*)(SCW + l * 4);
; #pragma unroll
;         for (int t = 0; t < 2; ++t) {
;             const int si = 2 * pi + t;
;             u32x2 w; w.x = 0u; w.y = 0u;
;             if (si <= li) {
;                 f32x4 d = (f32x4){0.f, 0.f, 0.f, 0.f};
; #pragma unroll
;                 for (int kk = 0; kk < 4; ++kk) d = __builtin_amdgcn_mfma_f32_16x16x32_bf16(SSD_FRAG(BS, PC, 16 * si, kk), cfr[kk], d, 0, 0, 0);
;                 float gv[4];
;                 const f32x4 acs_s = *(const LAS f32x4*)(SCW + (16 * si + 4 * q4) * 4), dt_s = *(const LAS f32x4*)(SCW + 256 + (16 * si + 4 * q4) * 4);
; #pragma unroll
;                 for (int e = 0; e < 4; ++e) gv[e] = d[e] * __expf(acs_l - acs_s[e]) * dt_s[e];
;                 if (si == li) {
; #pragma unroll
;                     for (int e = 0; e < 4; ++e) gv[e] = (4 * q4 + e <= c16) ? gv[e] : 0.f;
;                 }
;                 w.x = pk2(gv[0], gv[1]); w.y = pk2(gv[2], gv[3]);
;             }
.LBB0_742:
	ds_read_b128 v[70:73], v131
	ds_read_b128 v[66:69], v131 offset:64
	ds_read_b128 v[62:65], v131 offset:128
	ds_read_b128 v[58:61], v131 offset:192
	ds_read_b32 v76, v132
	v_mov_b32_e32 v100, 0
	s_and_b64 vcc, exec, s[22:23]
	v_mov_b32_e32 v101, v100
	s_cbranch_vccnz .LBB0_748
	ds_read_b128 v[100:103], v133 offset:17408
	ds_read_b128 v[148:151], v133 offset:17472
	ds_read_b128 v[176:179], v133 offset:17536
	ds_read_b128 v[180:183], v133 offset:17600
	ds_read_b128 v[184:187], v134
	ds_read_b128 v[152:155], v134 offset:256
	s_waitcnt lgkmcnt(5)
	v_mfma_f32_16x16x32_bf16 v[100:103], v[100:103], v[70:73], 0
	s_waitcnt lgkmcnt(4)
	v_mfma_f32_16x16x32_bf16 v[100:103], v[148:151], v[66:69], v[100:103]
	s_waitcnt lgkmcnt(3)
	v_mfma_f32_16x16x32_bf16 v[100:103], v[176:179], v[62:65], v[100:103]
	s_waitcnt lgkmcnt(2)
	v_mfma_f32_16x16x32_bf16 v[100:103], v[180:183], v[58:61], v[100:103]
	s_nop 1
	s_waitcnt lgkmcnt(1)
	v_sub_f32_e32 v104, v76, v184
	v_sub_f32_e32 v105, v76, v185
	v_mul_f32_e32 v104, 0x3fb8aa3b, v104
	v_mul_f32_e32 v105, 0x3fb8aa3b, v105
	v_exp_f32_e32 v104, v104
	v_exp_f32_e32 v105, v105
	s_nop 0
	v_pk_mul_f32 v[100:101], v[100:101], v[104:105]
	v_sub_f32_e32 v104, v76, v186
	v_sub_f32_e32 v105, v76, v187
	v_mul_f32_e32 v104, 0x3fb8aa3b, v104
	v_mul_f32_e32 v105, 0x3fb8aa3b, v105
	v_exp_f32_e32 v104, v104
	v_exp_f32_e32 v105, v105
	s_waitcnt lgkmcnt(0)
	v_pk_mul_f32 v[100:101], v[152:153], v[100:101]
	v_pk_mul_f32 v[102:103], v[102:103], v[104:105]
	s_nop 0
	v_pk_mul_f32 v[102:103], v[154:155], v[102:103]
	v_cndmask_b32_e64 v104, v100, 0, s[6:7]
	v_cndmask_b32_e64 v105, 0, v101, s[8:9]
	v_cndmask_b32_e64 v142, v102, 0, s[10:11]
	v_cndmask_b32_e64 v148, v103, 0, s[12:13]
	v_cndmask_b32_e64 v100, v100, v104, s[4:5]
	v_cndmask_b32_e64 v101, v101, v105, s[4:5]
	v_cndmask_b32_e64 v102, v102, v142, s[4:5]
	v_cndmask_b32_e64 v103, v103, v148, s[4:5]
	v_cvt_pk_bf16_f32 v100, v100, v101
	v_cvt_pk_bf16_f32 v101, v102, v103
	s_and_b64 vcc, exec, s[24:25]
	s_mov_b64 s[0:1], -1
	ds_write_b64 v144, v[100:101]
	s_cbranch_vccz .LBB0_749

; #define LAS __attribute__((address_space(3)))
; __device__ __forceinline__ unsigned pk2(float lo, float hi) { unsigned r; asm volatile("v_cvt_pk_bf16_f32 %0, %1, %2" : "=v"(r) : "v"(lo), "v"(hi)); return r; }
; template <bool DRY>
; __device__ __forceinline__ void ssd_chunk(SsdRegs& R, f32x4 (&st)[2], LAS unsigned char* L, bf16_t* BIG, const float* DT, float* SSQY, const SsdItem& I, int c, int tid, int lane, int wave, int li, int pi, int c16, int q4) {
;     ...
;             if (si <= li) {
;                 f32x4 d = (f32x4){0.f, 0.f, 0.f, 0.f};
; #pragma unroll
;                 for (int kk = 0; kk < 4; ++kk) d = __builtin_amdgcn_mfma_f32_16x16x32_bf16(SSD_FRAG(BS, PC, 16 * si, kk), cfr[kk], d, 0, 0, 0);
;                 float gv[4];
;                 const f32x4 acs_s = *(const LAS f32x4*)(SCW + (16 * si + 4 * q4) * 4), dt_s = *(const LAS f32x4*)(SCW + 256 + (16 * si + 4 * q4) * 4);
; #pragma unroll
;                 for (int e = 0; e < 4; ++e) gv[e] = d[e] * __expf(acs_l - acs_s[e]) * dt_s[e];
;                 if (si == li) {
; #pragma unroll
;                     for (int e = 0; e < 4; ++e) gv[e] = (4 * q4 + e <= c16) ? gv[e] : 0.f;
;                 }
;                 w.x = pk2(gv[0], gv[1]); w.y = pk2(gv[2], gv[3]);
;             }
.LBB0_745:
	ds_read_b128 v[100:103], v135 offset:17408
	ds_read_b128 v[148:151], v135 offset:17472
	ds_read_b128 v[176:179], v135 offset:17536
	ds_read_b128 v[180:183], v135 offset:17600
	ds_read_b128 v[184:187], v136
	ds_read_b128 v[152:155], v136 offset:256
	s_waitcnt lgkmcnt(5)
	v_mfma_f32_16x16x32_bf16 v[100:103], v[100:103], v[70:73], 0
	s_waitcnt lgkmcnt(4)
	v_mfma_f32_16x16x32_bf16 v[100:103], v[148:151], v[66:69], v[100:103]
	s_waitcnt lgkmcnt(3)
	v_mfma_f32_16x16x32_bf16 v[100:103], v[176:179], v[62:65], v[100:103]
	s_waitcnt lgkmcnt(2)
	v_mfma_f32_16x16x32_bf16 v[100:103], v[180:183], v[58:61], v[100:103]
	s_nop 1
	s_waitcnt lgkmcnt(1)
	v_sub_f32_e32 v104, v76, v184
	v_sub_f32_e32 v105, v76, v185
	v_mul_f32_e32 v104, 0x3fb8aa3b, v104
	v_mul_f32_e32 v105, 0x3fb8aa3b, v105
	v_exp_f32_e32 v104, v104
	v_exp_f32_e32 v105, v105
	s_nop 0
	v_pk_mul_f32 v[100:101], v[100:101], v[104:105]
	v_sub_f32_e32 v104, v76, v186
	v_sub_f32_e32 v76, v76, v187
	v_mul_f32_e32 v104, 0x3fb8aa3b, v104
	v_mul_f32_e32 v76, 0x3fb8aa3b, v76
	v_exp_f32_e32 v104, v104
	v_exp_f32_e32 v105, v76
	s_waitcnt lgkmcnt(0)
	v_pk_mul_f32 v[100:101], v[152:153], v[100:101]
	v_pk_mul_f32 v[102:103], v[102:103], v[104:105]
	s_nop 0
	v_pk_mul_f32 v[102:103], v[154:155], v[102:103]
	v_cndmask_b32_e64 v76, v100, 0, s[6:7]
	v_cndmask_b32_e64 v104, 0, v101, s[8:9]
	v_cndmask_b32_e64 v105, v102, 0, s[10:11]
	v_cndmask_b32_e64 v142, v103, 0, s[12:13]
	v_cndmask_b32_e64 v76, v100, v76, s[14:15]
	v_cndmask_b32_e64 v100, v101, v104, s[14:15]
	v_cndmask_b32_e64 v102, v102, v105, s[14:15]
	v_cndmask_b32_e64 v103, v103, v142, s[14:15]
	v_cvt_pk_bf16_f32 v100, v76, v100
	v_cvt_pk_bf16_f32 v101, v102, v103
